# GEMM unit heads: accumulators cleared with 64 v_mov_b64 instead of 128 v_mov_b32
# speedup vs baseline: 1.0059x; 1.0059x over previous
.LBB0_154:
	s_ashr_i32 s15, s14, 31
	v_cmp_lt_i64_e32 vcc, s[16:17], v[142:143]
	s_lshl_b64 s[16:17], s[14:15], 19
	s_add_u32 s16, s44, s16
	s_addc_u32 s17, s45, s17
	s_and_b64 s[18:19], vcc, exec
	s_cselect_b32 s15, s17, s21
	s_cselect_b32 s82, s16, s20
	s_ashr_i32 s13, s12, 31
	s_lshl_b64 s[18:19], s[12:13], 19
	s_add_u32 s18, s60, s18
	s_addc_u32 s19, s61, s19
	s_and_b64 s[28:29], vcc, exec
	s_cselect_b32 s13, s19, s27
	s_cselect_b32 s83, s18, s26
	s_add_u32 s20, s20, 0x40080
	s_addc_u32 s21, s21, 0
	s_add_u32 s84, s26, 0x100
	v_mov_b64_e32 v[0:1], 0
	v_mov_b64_e32 v[2:3], 0
	v_mov_b64_e32 v[4:5], 0
	v_mov_b64_e32 v[6:7], 0
	v_mov_b64_e32 v[8:9], 0
	v_mov_b64_e32 v[10:11], 0
	v_mov_b64_e32 v[12:13], 0
	v_mov_b64_e32 v[14:15], 0
	v_mov_b64_e32 v[16:17], 0
	v_mov_b64_e32 v[18:19], 0
	v_mov_b64_e32 v[20:21], 0
	v_mov_b64_e32 v[22:23], 0
	v_mov_b64_e32 v[24:25], 0
	v_mov_b64_e32 v[26:27], 0
	v_mov_b64_e32 v[28:29], 0
	v_mov_b64_e32 v[30:31], 0
	v_mov_b64_e32 v[32:33], 0
	v_mov_b64_e32 v[34:35], 0
	v_mov_b64_e32 v[36:37], 0
	v_mov_b64_e32 v[38:39], 0
	v_mov_b64_e32 v[40:41], 0
	v_mov_b64_e32 v[42:43], 0
	v_mov_b64_e32 v[44:45], 0
	v_mov_b64_e32 v[46:47], 0
	v_mov_b64_e32 v[48:49], 0
	v_mov_b64_e32 v[50:51], 0
	v_mov_b64_e32 v[52:53], 0
	v_mov_b64_e32 v[54:55], 0
	v_mov_b64_e32 v[56:57], 0
	v_mov_b64_e32 v[58:59], 0
	v_mov_b64_e32 v[60:61], 0
	v_mov_b64_e32 v[62:63], 0
	v_mov_b64_e32 v[64:65], 0
	v_mov_b64_e32 v[66:67], 0
	v_mov_b64_e32 v[68:69], 0
	v_mov_b64_e32 v[70:71], 0
	v_mov_b64_e32 v[72:73], 0
	v_mov_b64_e32 v[74:75], 0
	v_mov_b64_e32 v[76:77], 0
	v_mov_b64_e32 v[78:79], 0
	v_mov_b64_e32 v[80:81], 0
	v_mov_b64_e32 v[82:83], 0
	v_mov_b64_e32 v[84:85], 0
	v_mov_b64_e32 v[86:87], 0
	v_mov_b64_e32 v[88:89], 0
	v_mov_b64_e32 v[90:91], 0
	v_mov_b64_e32 v[92:93], 0
	v_mov_b64_e32 v[94:95], 0
	v_mov_b64_e32 v[96:97], 0
	v_mov_b64_e32 v[98:99], 0
	v_mov_b64_e32 v[100:101], 0
	v_mov_b64_e32 v[102:103], 0
	v_mov_b64_e32 v[104:105], 0
	v_mov_b64_e32 v[106:107], 0
	v_mov_b64_e32 v[108:109], 0
	v_mov_b64_e32 v[110:111], 0
	v_mov_b64_e32 v[112:113], 0
	v_mov_b64_e32 v[114:115], 0
	v_mov_b64_e32 v[116:117], 0
	v_mov_b64_e32 v[118:119], 0
	v_mov_b64_e32 v[120:121], 0
	v_mov_b64_e32 v[122:123], 0
	v_mov_b64_e32 v[124:125], 0
	v_mov_b64_e32 v[126:127], 0
	s_addc_u32 s85, s27, 0
	s_mov_b32 s86, -2

.LBB0_485:
	s_ashr_i32 s19, s18, 31
	v_cmp_lt_i64_e32 vcc, s[20:21], v[142:143]
	s_lshl_b64 s[20:21], s[18:19], 19
	s_add_u32 s20, s44, s20
	s_addc_u32 s21, s45, s21
	s_and_b64 s[26:27], vcc, exec
	s_cselect_b32 s19, s21, s29
	s_cselect_b32 s80, s20, s28
	s_ashr_i32 s17, s16, 31
	s_lshl_b64 s[26:27], s[16:17], 19
	s_add_u32 s26, s62, s26
	s_addc_u32 s27, s63, s27
	s_and_b64 s[34:35], vcc, exec
	s_cselect_b32 s17, s27, s31
	s_cselect_b32 s81, s26, s30
	s_add_u32 s28, s28, 0x40080
	s_addc_u32 s29, s29, 0
	s_add_u32 s82, s30, 0x100
	v_mov_b64_e32 v[0:1], 0
	v_mov_b64_e32 v[2:3], 0
	v_mov_b64_e32 v[4:5], 0
	v_mov_b64_e32 v[6:7], 0
	v_mov_b64_e32 v[8:9], 0
	v_mov_b64_e32 v[10:11], 0
	v_mov_b64_e32 v[12:13], 0
	v_mov_b64_e32 v[14:15], 0
	v_mov_b64_e32 v[16:17], 0
	v_mov_b64_e32 v[18:19], 0
	v_mov_b64_e32 v[20:21], 0
	v_mov_b64_e32 v[22:23], 0
	v_mov_b64_e32 v[24:25], 0
	v_mov_b64_e32 v[26:27], 0
	v_mov_b64_e32 v[28:29], 0
	v_mov_b64_e32 v[30:31], 0
	v_mov_b64_e32 v[32:33], 0
	v_mov_b64_e32 v[34:35], 0
	v_mov_b64_e32 v[36:37], 0
	v_mov_b64_e32 v[38:39], 0
	v_mov_b64_e32 v[40:41], 0
	v_mov_b64_e32 v[42:43], 0
	v_mov_b64_e32 v[44:45], 0
	v_mov_b64_e32 v[46:47], 0
	v_mov_b64_e32 v[48:49], 0
	v_mov_b64_e32 v[50:51], 0
	v_mov_b64_e32 v[52:53], 0
	v_mov_b64_e32 v[54:55], 0
	v_mov_b64_e32 v[56:57], 0
	v_mov_b64_e32 v[58:59], 0
	v_mov_b64_e32 v[60:61], 0
	v_mov_b64_e32 v[62:63], 0
	v_mov_b64_e32 v[64:65], 0
	v_mov_b64_e32 v[66:67], 0
	v_mov_b64_e32 v[68:69], 0
	v_mov_b64_e32 v[70:71], 0
	v_mov_b64_e32 v[72:73], 0
	v_mov_b64_e32 v[74:75], 0
	v_mov_b64_e32 v[76:77], 0
	v_mov_b64_e32 v[78:79], 0
	v_mov_b64_e32 v[80:81], 0
	v_mov_b64_e32 v[82:83], 0
	v_mov_b64_e32 v[84:85], 0
	v_mov_b64_e32 v[86:87], 0
	v_mov_b64_e32 v[88:89], 0
	v_mov_b64_e32 v[90:91], 0
	v_mov_b64_e32 v[92:93], 0
	v_mov_b64_e32 v[94:95], 0
	v_mov_b64_e32 v[96:97], 0
	v_mov_b64_e32 v[98:99], 0
	v_mov_b64_e32 v[100:101], 0
	v_mov_b64_e32 v[102:103], 0
	v_mov_b64_e32 v[104:105], 0
	v_mov_b64_e32 v[106:107], 0
	v_mov_b64_e32 v[108:109], 0
	v_mov_b64_e32 v[110:111], 0
	v_mov_b64_e32 v[112:113], 0
	v_mov_b64_e32 v[114:115], 0
	v_mov_b64_e32 v[116:117], 0
	v_mov_b64_e32 v[118:119], 0
	v_mov_b64_e32 v[120:121], 0
	v_mov_b64_e32 v[122:123], 0
	v_mov_b64_e32 v[124:125], 0
	v_mov_b64_e32 v[126:127], 0
	s_addc_u32 s83, s31, 0
	s_mov_b32 s84, -2

.LBB0_682:
	s_ashr_i32 s19, s18, 31
	v_cmp_lt_i64_e32 vcc, s[20:21], v[142:143]
	s_lshl_b64 s[20:21], s[18:19], 19
	s_add_u32 s20, s44, s20
	s_addc_u32 s21, s45, s21
	s_and_b64 s[26:27], vcc, exec
	s_cselect_b32 s19, s21, s31
	s_cselect_b32 s81, s20, s30
	s_ashr_i32 s17, s16, 31
	s_lshl_b64 s[26:27], s[16:17], 19
	s_add_u32 s26, s64, s26
	s_addc_u32 s27, s65, s27
	s_and_b64 s[54:55], vcc, exec
	s_cselect_b32 s17, s27, s35
	s_cselect_b32 s82, s26, s34
	s_add_u32 s30, s30, 0x40080
	s_addc_u32 s31, s31, 0
	s_add_u32 s83, s34, 0x100
	v_mov_b64_e32 v[0:1], 0
	v_mov_b64_e32 v[2:3], 0
	v_mov_b64_e32 v[4:5], 0
	v_mov_b64_e32 v[6:7], 0
	v_mov_b64_e32 v[8:9], 0
	v_mov_b64_e32 v[10:11], 0
	v_mov_b64_e32 v[12:13], 0
	v_mov_b64_e32 v[14:15], 0
	v_mov_b64_e32 v[16:17], 0
	v_mov_b64_e32 v[18:19], 0
	v_mov_b64_e32 v[20:21], 0
	v_mov_b64_e32 v[22:23], 0
	v_mov_b64_e32 v[24:25], 0
	v_mov_b64_e32 v[26:27], 0
	v_mov_b64_e32 v[28:29], 0
	v_mov_b64_e32 v[30:31], 0
	v_mov_b64_e32 v[32:33], 0
	v_mov_b64_e32 v[34:35], 0
	v_mov_b64_e32 v[36:37], 0
	v_mov_b64_e32 v[38:39], 0
	v_mov_b64_e32 v[40:41], 0
	v_mov_b64_e32 v[42:43], 0
	v_mov_b64_e32 v[44:45], 0
	v_mov_b64_e32 v[46:47], 0
	v_mov_b64_e32 v[48:49], 0
	v_mov_b64_e32 v[50:51], 0
	v_mov_b64_e32 v[52:53], 0
	v_mov_b64_e32 v[54:55], 0
	v_mov_b64_e32 v[56:57], 0
	v_mov_b64_e32 v[58:59], 0
	v_mov_b64_e32 v[60:61], 0
	v_mov_b64_e32 v[62:63], 0
	v_mov_b64_e32 v[64:65], 0
	v_mov_b64_e32 v[66:67], 0
	v_mov_b64_e32 v[68:69], 0
	v_mov_b64_e32 v[70:71], 0
	v_mov_b64_e32 v[72:73], 0
	v_mov_b64_e32 v[74:75], 0
	v_mov_b64_e32 v[76:77], 0
	v_mov_b64_e32 v[78:79], 0
	v_mov_b64_e32 v[80:81], 0
	v_mov_b64_e32 v[82:83], 0
	v_mov_b64_e32 v[84:85], 0
	v_mov_b64_e32 v[86:87], 0
	v_mov_b64_e32 v[88:89], 0
	v_mov_b64_e32 v[90:91], 0
	v_mov_b64_e32 v[92:93], 0
	v_mov_b64_e32 v[94:95], 0
	v_mov_b64_e32 v[96:97], 0
	v_mov_b64_e32 v[98:99], 0
	v_mov_b64_e32 v[100:101], 0
	v_mov_b64_e32 v[102:103], 0
	v_mov_b64_e32 v[104:105], 0
	v_mov_b64_e32 v[106:107], 0
	v_mov_b64_e32 v[108:109], 0
	v_mov_b64_e32 v[110:111], 0
	v_mov_b64_e32 v[112:113], 0
	v_mov_b64_e32 v[114:115], 0
	v_mov_b64_e32 v[116:117], 0
	v_mov_b64_e32 v[118:119], 0
	v_mov_b64_e32 v[120:121], 0
	v_mov_b64_e32 v[122:123], 0
	v_mov_b64_e32 v[124:125], 0
	v_mov_b64_e32 v[126:127], 0
	s_addc_u32 s84, s35, 0
	s_mov_b32 s85, -2

.LBB0_775:
	s_ashr_i32 s21, s20, 31
	v_cmp_lt_i64_e32 vcc, s[26:27], v[142:143]
	s_lshl_b64 s[26:27], s[20:21], 21
	s_add_u32 s26, s46, s26
	s_addc_u32 s27, s47, s27
	s_and_b64 s[28:29], vcc, exec
	s_cselect_b32 s21, s27, s31
	s_cselect_b32 s81, s26, s30
	s_ashr_i32 s19, s18, 31
	s_lshl_b64 s[28:29], s[18:19], 21
	s_add_u32 s28, s66, s28
	s_addc_u32 s29, s67, s29
	s_and_b64 s[54:55], vcc, exec
	s_cselect_b32 s19, s29, s35
	s_cselect_b32 s82, s28, s34
	s_add_u32 s30, s30, 0x100080
	s_addc_u32 s31, s31, 0
	s_add_u32 s83, s34, 0x100
	v_mov_b64_e32 v[0:1], 0
	v_mov_b64_e32 v[2:3], 0
	v_mov_b64_e32 v[4:5], 0
	v_mov_b64_e32 v[6:7], 0
	v_mov_b64_e32 v[8:9], 0
	v_mov_b64_e32 v[10:11], 0
	v_mov_b64_e32 v[12:13], 0
	v_mov_b64_e32 v[14:15], 0
	v_mov_b64_e32 v[16:17], 0
	v_mov_b64_e32 v[18:19], 0
	v_mov_b64_e32 v[20:21], 0
	v_mov_b64_e32 v[22:23], 0
	v_mov_b64_e32 v[24:25], 0
	v_mov_b64_e32 v[26:27], 0
	v_mov_b64_e32 v[28:29], 0
	v_mov_b64_e32 v[30:31], 0
	v_mov_b64_e32 v[32:33], 0
	v_mov_b64_e32 v[34:35], 0
	v_mov_b64_e32 v[36:37], 0
	v_mov_b64_e32 v[38:39], 0
	v_mov_b64_e32 v[40:41], 0
	v_mov_b64_e32 v[42:43], 0
	v_mov_b64_e32 v[44:45], 0
	v_mov_b64_e32 v[46:47], 0
	v_mov_b64_e32 v[48:49], 0
	v_mov_b64_e32 v[50:51], 0
	v_mov_b64_e32 v[52:53], 0
	v_mov_b64_e32 v[54:55], 0
	v_mov_b64_e32 v[56:57], 0
	v_mov_b64_e32 v[58:59], 0
	v_mov_b64_e32 v[60:61], 0
	v_mov_b64_e32 v[62:63], 0
	v_mov_b64_e32 v[64:65], 0
	v_mov_b64_e32 v[66:67], 0
	v_mov_b64_e32 v[68:69], 0
	v_mov_b64_e32 v[70:71], 0
	v_mov_b64_e32 v[72:73], 0
	v_mov_b64_e32 v[74:75], 0
	v_mov_b64_e32 v[76:77], 0
	v_mov_b64_e32 v[78:79], 0
	v_mov_b64_e32 v[80:81], 0
	v_mov_b64_e32 v[82:83], 0
	v_mov_b64_e32 v[84:85], 0
	v_mov_b64_e32 v[86:87], 0
	v_mov_b64_e32 v[88:89], 0
	v_mov_b64_e32 v[90:91], 0
	v_mov_b64_e32 v[92:93], 0
	v_mov_b64_e32 v[94:95], 0
	v_mov_b64_e32 v[96:97], 0
	v_mov_b64_e32 v[98:99], 0
	v_mov_b64_e32 v[100:101], 0
	v_mov_b64_e32 v[102:103], 0
	v_mov_b64_e32 v[104:105], 0
	v_mov_b64_e32 v[106:107], 0
	v_mov_b64_e32 v[108:109], 0
	v_mov_b64_e32 v[110:111], 0
	v_mov_b64_e32 v[112:113], 0
	v_mov_b64_e32 v[114:115], 0
	v_mov_b64_e32 v[116:117], 0
	v_mov_b64_e32 v[118:119], 0
	v_mov_b64_e32 v[120:121], 0
	v_mov_b64_e32 v[122:123], 0
	v_mov_b64_e32 v[124:125], 0
	v_mov_b64_e32 v[126:127], 0
	s_addc_u32 s84, s35, 0
	s_mov_b32 s85, -2

.LBB0_911:
	s_ashr_i32 s27, s26, 31
	v_cmp_lt_i64_e32 vcc, s[28:29], v[142:143]
	s_lshl_b64 s[28:29], s[26:27], 19
	s_add_u32 s28, s44, s28
	s_addc_u32 s29, s45, s29
	s_and_b64 s[30:31], vcc, exec
	s_cselect_b32 s27, s29, s35
	s_cselect_b32 s83, s28, s34
	s_ashr_i32 s21, s20, 31
	s_lshl_b64 s[30:31], s[20:21], 19
	s_add_u32 s30, s36, s30
	s_addc_u32 s31, s37, s31
	s_and_b64 s[56:57], vcc, exec
	s_cselect_b32 s21, s31, s55
	s_cselect_b32 s84, s30, s54
	s_add_u32 s34, s34, 0x40080
	s_addc_u32 s35, s35, 0
	s_add_u32 s85, s54, 0x100
	v_mov_b64_e32 v[0:1], 0
	v_mov_b64_e32 v[2:3], 0
	v_mov_b64_e32 v[4:5], 0
	v_mov_b64_e32 v[6:7], 0
	v_mov_b64_e32 v[8:9], 0
	v_mov_b64_e32 v[10:11], 0
	v_mov_b64_e32 v[12:13], 0
	v_mov_b64_e32 v[14:15], 0
	v_mov_b64_e32 v[16:17], 0
	v_mov_b64_e32 v[18:19], 0
	v_mov_b64_e32 v[20:21], 0
	v_mov_b64_e32 v[22:23], 0
	v_mov_b64_e32 v[24:25], 0
	v_mov_b64_e32 v[26:27], 0
	v_mov_b64_e32 v[28:29], 0
	v_mov_b64_e32 v[30:31], 0
	v_mov_b64_e32 v[32:33], 0
	v_mov_b64_e32 v[34:35], 0
	v_mov_b64_e32 v[36:37], 0
	v_mov_b64_e32 v[38:39], 0
	v_mov_b64_e32 v[40:41], 0
	v_mov_b64_e32 v[42:43], 0
	v_mov_b64_e32 v[44:45], 0
	v_mov_b64_e32 v[46:47], 0
	v_mov_b64_e32 v[48:49], 0
	v_mov_b64_e32 v[50:51], 0
	v_mov_b64_e32 v[52:53], 0
	v_mov_b64_e32 v[54:55], 0
	v_mov_b64_e32 v[56:57], 0
	v_mov_b64_e32 v[58:59], 0
	v_mov_b64_e32 v[60:61], 0
	v_mov_b64_e32 v[62:63], 0
	v_mov_b64_e32 v[64:65], 0
	v_mov_b64_e32 v[66:67], 0
	v_mov_b64_e32 v[68:69], 0
	v_mov_b64_e32 v[70:71], 0
	v_mov_b64_e32 v[72:73], 0
	v_mov_b64_e32 v[74:75], 0
	v_mov_b64_e32 v[76:77], 0
	v_mov_b64_e32 v[78:79], 0
	v_mov_b64_e32 v[80:81], 0
	v_mov_b64_e32 v[82:83], 0
	v_mov_b64_e32 v[84:85], 0
	v_mov_b64_e32 v[86:87], 0
	v_mov_b64_e32 v[88:89], 0
	v_mov_b64_e32 v[90:91], 0
	v_mov_b64_e32 v[92:93], 0
	v_mov_b64_e32 v[94:95], 0
	v_mov_b64_e32 v[96:97], 0
	v_mov_b64_e32 v[98:99], 0
	v_mov_b64_e32 v[100:101], 0
	v_mov_b64_e32 v[102:103], 0
	v_mov_b64_e32 v[104:105], 0
	v_mov_b64_e32 v[106:107], 0
	v_mov_b64_e32 v[108:109], 0
	v_mov_b64_e32 v[110:111], 0
	v_mov_b64_e32 v[112:113], 0
	v_mov_b64_e32 v[114:115], 0
	v_mov_b64_e32 v[116:117], 0
	v_mov_b64_e32 v[118:119], 0
	v_mov_b64_e32 v[120:121], 0
	v_mov_b64_e32 v[122:123], 0
	v_mov_b64_e32 v[124:125], 0
	v_mov_b64_e32 v[126:127], 0
	s_addc_u32 s86, s55, 0
	s_mov_b32 s87, -2

.LBB0_1290:
	s_ashr_i32 s21, s20, 31
	v_cmp_lt_i64_e32 vcc, s[26:27], v[142:143]
	s_lshl_b64 s[26:27], s[20:21], 19
	s_add_u32 s26, s44, s26
	s_addc_u32 s27, s45, s27
	s_and_b64 s[28:29], vcc, exec
	s_cselect_b32 s21, s27, s35
	s_cselect_b32 s75, s26, s34
	s_ashr_i32 s19, s18, 31
	s_lshl_b64 s[28:29], s[18:19], 19
	s_add_u32 s28, s42, s28
	s_addc_u32 s29, s43, s29
	s_and_b64 s[38:39], vcc, exec
	s_cselect_b32 s19, s29, s37
	s_cselect_b32 s76, s28, s36
	s_add_u32 s34, s34, 0x40080
	s_addc_u32 s35, s35, 0
	s_add_u32 s77, s36, 0x100
	v_mov_b64_e32 v[0:1], 0
	v_mov_b64_e32 v[2:3], 0
	v_mov_b64_e32 v[4:5], 0
	v_mov_b64_e32 v[6:7], 0
	v_mov_b64_e32 v[8:9], 0
	v_mov_b64_e32 v[10:11], 0
	v_mov_b64_e32 v[12:13], 0
	v_mov_b64_e32 v[14:15], 0
	v_mov_b64_e32 v[16:17], 0
	v_mov_b64_e32 v[18:19], 0
	v_mov_b64_e32 v[20:21], 0
	v_mov_b64_e32 v[22:23], 0
	v_mov_b64_e32 v[24:25], 0
	v_mov_b64_e32 v[26:27], 0
	v_mov_b64_e32 v[28:29], 0
	v_mov_b64_e32 v[30:31], 0
	v_mov_b64_e32 v[32:33], 0
	v_mov_b64_e32 v[34:35], 0
	v_mov_b64_e32 v[36:37], 0
	v_mov_b64_e32 v[38:39], 0
	v_mov_b64_e32 v[40:41], 0
	v_mov_b64_e32 v[42:43], 0
	v_mov_b64_e32 v[44:45], 0
	v_mov_b64_e32 v[46:47], 0
	v_mov_b64_e32 v[48:49], 0
	v_mov_b64_e32 v[50:51], 0
	v_mov_b64_e32 v[52:53], 0
	v_mov_b64_e32 v[54:55], 0
	v_mov_b64_e32 v[56:57], 0
	v_mov_b64_e32 v[58:59], 0
	v_mov_b64_e32 v[60:61], 0
	v_mov_b64_e32 v[62:63], 0
	v_mov_b64_e32 v[64:65], 0
	v_mov_b64_e32 v[66:67], 0
	v_mov_b64_e32 v[68:69], 0
	v_mov_b64_e32 v[70:71], 0
	v_mov_b64_e32 v[72:73], 0
	v_mov_b64_e32 v[74:75], 0
	v_mov_b64_e32 v[76:77], 0
	v_mov_b64_e32 v[78:79], 0
	v_mov_b64_e32 v[80:81], 0
	v_mov_b64_e32 v[82:83], 0
	v_mov_b64_e32 v[84:85], 0
	v_mov_b64_e32 v[86:87], 0
	v_mov_b64_e32 v[88:89], 0
	v_mov_b64_e32 v[90:91], 0
	v_mov_b64_e32 v[92:93], 0
	v_mov_b64_e32 v[94:95], 0
	v_mov_b64_e32 v[96:97], 0
	v_mov_b64_e32 v[98:99], 0
	v_mov_b64_e32 v[100:101], 0
	v_mov_b64_e32 v[102:103], 0
	v_mov_b64_e32 v[104:105], 0
	v_mov_b64_e32 v[106:107], 0
	v_mov_b64_e32 v[108:109], 0
	v_mov_b64_e32 v[110:111], 0
	v_mov_b64_e32 v[112:113], 0
	v_mov_b64_e32 v[114:115], 0
	v_mov_b64_e32 v[116:117], 0
	v_mov_b64_e32 v[118:119], 0
	v_mov_b64_e32 v[120:121], 0
	v_mov_b64_e32 v[122:123], 0
	v_mov_b64_e32 v[124:125], 0
	v_mov_b64_e32 v[126:127], 0
	s_addc_u32 s78, s37, 0
	s_mov_b32 s79, -2

.LBB0_1309:
	s_ashr_i32 s27, s26, 31
	v_cmp_lt_i64_e32 vcc, s[28:29], v[142:143]
	s_lshl_b64 s[28:29], s[26:27], 19
	s_add_u32 s28, s44, s28
	s_addc_u32 s29, s45, s29
	s_and_b64 s[30:31], vcc, exec
	s_cselect_b32 s27, s29, s37
	s_cselect_b32 s73, s28, s36
	s_ashr_i32 s21, s20, 31
	s_lshl_b64 s[30:31], s[20:21], 19
	s_add_u32 s30, s8, s30
	s_addc_u32 s31, s9, s31
	s_and_b64 s[40:41], vcc, exec
	s_cselect_b32 s21, s31, s39
	s_cselect_b32 s74, s30, s38
	s_add_u32 s36, s36, 0x40080
	s_addc_u32 s37, s37, 0
	s_add_u32 s75, s38, 0x100
	v_mov_b64_e32 v[0:1], 0
	v_mov_b64_e32 v[2:3], 0
	v_mov_b64_e32 v[4:5], 0
	v_mov_b64_e32 v[6:7], 0
	v_mov_b64_e32 v[8:9], 0
	v_mov_b64_e32 v[10:11], 0
	v_mov_b64_e32 v[12:13], 0
	v_mov_b64_e32 v[14:15], 0
	v_mov_b64_e32 v[16:17], 0
	v_mov_b64_e32 v[18:19], 0
	v_mov_b64_e32 v[20:21], 0
	v_mov_b64_e32 v[22:23], 0
	v_mov_b64_e32 v[24:25], 0
	v_mov_b64_e32 v[26:27], 0
	v_mov_b64_e32 v[28:29], 0
	v_mov_b64_e32 v[30:31], 0
	v_mov_b64_e32 v[32:33], 0
	v_mov_b64_e32 v[34:35], 0
	v_mov_b64_e32 v[36:37], 0
	v_mov_b64_e32 v[38:39], 0
	v_mov_b64_e32 v[40:41], 0
	v_mov_b64_e32 v[42:43], 0
	v_mov_b64_e32 v[44:45], 0
	v_mov_b64_e32 v[46:47], 0
	v_mov_b64_e32 v[48:49], 0
	v_mov_b64_e32 v[50:51], 0
	v_mov_b64_e32 v[52:53], 0
	v_mov_b64_e32 v[54:55], 0
	v_mov_b64_e32 v[56:57], 0
	v_mov_b64_e32 v[58:59], 0
	v_mov_b64_e32 v[60:61], 0
	v_mov_b64_e32 v[62:63], 0
	v_mov_b64_e32 v[64:65], 0
	v_mov_b64_e32 v[66:67], 0
	v_mov_b64_e32 v[68:69], 0
	v_mov_b64_e32 v[70:71], 0
	v_mov_b64_e32 v[72:73], 0
	v_mov_b64_e32 v[74:75], 0
	v_mov_b64_e32 v[76:77], 0
	v_mov_b64_e32 v[78:79], 0
	v_mov_b64_e32 v[80:81], 0
	v_mov_b64_e32 v[82:83], 0
	v_mov_b64_e32 v[84:85], 0
	v_mov_b64_e32 v[86:87], 0
	v_mov_b64_e32 v[88:89], 0
	v_mov_b64_e32 v[90:91], 0
	v_mov_b64_e32 v[92:93], 0
	v_mov_b64_e32 v[94:95], 0
	v_mov_b64_e32 v[96:97], 0
	v_mov_b64_e32 v[98:99], 0
	v_mov_b64_e32 v[100:101], 0
	v_mov_b64_e32 v[102:103], 0
	v_mov_b64_e32 v[104:105], 0
	v_mov_b64_e32 v[106:107], 0
	v_mov_b64_e32 v[108:109], 0
	v_mov_b64_e32 v[110:111], 0
	v_mov_b64_e32 v[112:113], 0
	v_mov_b64_e32 v[114:115], 0
	v_mov_b64_e32 v[116:117], 0
	v_mov_b64_e32 v[118:119], 0
	v_mov_b64_e32 v[120:121], 0
	v_mov_b64_e32 v[122:123], 0
	v_mov_b64_e32 v[124:125], 0
	v_mov_b64_e32 v[126:127], 0
	s_addc_u32 s76, s39, 0
	s_mov_b32 s77, -2

.LBB0_1383:
	s_ashr_i32 s27, s26, 31
	v_cmp_lt_i64_e32 vcc, s[28:29], v[142:143]
	s_lshl_b64 s[28:29], s[26:27], 21
	s_add_u32 s28, s46, s28
	s_addc_u32 s29, s47, s29
	s_and_b64 s[30:31], vcc, exec
	s_cselect_b32 s27, s29, s35
	s_cselect_b32 s73, s28, s34
	s_ashr_i32 s21, s20, 31
	s_lshl_b64 s[30:31], s[20:21], 21
	s_add_u32 s30, s41, s30
	s_addc_u32 s31, s42, s31
	s_and_b64 s[38:39], vcc, exec
	s_cselect_b32 s21, s31, s37
	s_cselect_b32 s74, s30, s36
	s_add_u32 s34, s34, 0x100080
	s_addc_u32 s35, s35, 0
	s_add_u32 s75, s36, 0x100
	v_mov_b64_e32 v[0:1], 0
	v_mov_b64_e32 v[2:3], 0
	v_mov_b64_e32 v[4:5], 0
	v_mov_b64_e32 v[6:7], 0
	v_mov_b64_e32 v[8:9], 0
	v_mov_b64_e32 v[10:11], 0
	v_mov_b64_e32 v[12:13], 0
	v_mov_b64_e32 v[14:15], 0
	v_mov_b64_e32 v[16:17], 0
	v_mov_b64_e32 v[18:19], 0
	v_mov_b64_e32 v[20:21], 0
	v_mov_b64_e32 v[22:23], 0
	v_mov_b64_e32 v[24:25], 0
	v_mov_b64_e32 v[26:27], 0
	v_mov_b64_e32 v[28:29], 0
	v_mov_b64_e32 v[30:31], 0
	v_mov_b64_e32 v[32:33], 0
	v_mov_b64_e32 v[34:35], 0
	v_mov_b64_e32 v[36:37], 0
	v_mov_b64_e32 v[38:39], 0
	v_mov_b64_e32 v[40:41], 0
	v_mov_b64_e32 v[42:43], 0
	v_mov_b64_e32 v[44:45], 0
	v_mov_b64_e32 v[46:47], 0
	v_mov_b64_e32 v[48:49], 0
	v_mov_b64_e32 v[50:51], 0
	v_mov_b64_e32 v[52:53], 0
	v_mov_b64_e32 v[54:55], 0
	v_mov_b64_e32 v[56:57], 0
	v_mov_b64_e32 v[58:59], 0
	v_mov_b64_e32 v[60:61], 0
	v_mov_b64_e32 v[62:63], 0
	v_mov_b64_e32 v[64:65], 0
	v_mov_b64_e32 v[66:67], 0
	v_mov_b64_e32 v[68:69], 0
	v_mov_b64_e32 v[70:71], 0
	v_mov_b64_e32 v[72:73], 0
	v_mov_b64_e32 v[74:75], 0
	v_mov_b64_e32 v[76:77], 0
	v_mov_b64_e32 v[78:79], 0
	v_mov_b64_e32 v[80:81], 0
	v_mov_b64_e32 v[82:83], 0
	v_mov_b64_e32 v[84:85], 0
	v_mov_b64_e32 v[86:87], 0
	v_mov_b64_e32 v[88:89], 0
	v_mov_b64_e32 v[90:91], 0
	v_mov_b64_e32 v[92:93], 0
	v_mov_b64_e32 v[94:95], 0
	v_mov_b64_e32 v[96:97], 0
	v_mov_b64_e32 v[98:99], 0
	v_mov_b64_e32 v[100:101], 0
	v_mov_b64_e32 v[102:103], 0
	v_mov_b64_e32 v[104:105], 0
	v_mov_b64_e32 v[106:107], 0
	v_mov_b64_e32 v[108:109], 0
	v_mov_b64_e32 v[110:111], 0
	v_mov_b64_e32 v[112:113], 0
	v_mov_b64_e32 v[114:115], 0
	v_mov_b64_e32 v[116:117], 0
	v_mov_b64_e32 v[118:119], 0
	v_mov_b64_e32 v[120:121], 0
	v_mov_b64_e32 v[122:123], 0
	v_mov_b64_e32 v[124:125], 0
	v_mov_b64_e32 v[126:127], 0
	s_addc_u32 s76, s37, 0
	s_mov_b32 s77, -2
